# MLA tile loop: L2-warming dummy loads of K/V/k-rope rows two tiles ahead (on top of v12)
# speedup vs baseline: 1.0123x; 1.0123x over previous
; #define LAS __attribute__((address_space(3)))
; DI void mla_item(int g_wave, LAS unsigned char* lds, const bf16_t* QN, const bf16_t* QR, const bf16_t* KN, const bf16_t* KRb, const bf16_t* VM, bf16_t* MIX,
;                  int kvbase, int qrow0, int nq, int head, int ntiles, int wt) {
;     ...
;     MLA_LOAD(0); MLA_STORE(0);
;     __syncthreads();
;     float m_run = -1e30f, l_run = 0.f;
;     f32x16 o0, o1;
; #pragma unroll
;     for (int i = 0; i < 16; ++i) { o0[i] = 0.f; o1[i] = 0.f; }
;     const int i16 = lane & 15, tq = i16 >> 2, tp = i16 & 3, blk = (lane >> 4) & 1;
;     for (int T = 0; T < ntiles; ++T) {
;         if (T + 1 < ntiles) MLA_LOAD(T + 1);
;         if (T < wt) {
;             LAS const unsigned char* base = lds + (T & 1) * BUF;
;             f32x16 s0, s1;
; #pragma unroll
;             for (int i = 0; i < 16; ++i) { s0[i] = 0.f; s1[i] = 0.f; }
; #pragma unroll
;             for (int s = 0; s < 6; ++s) {
;                 const bf16x8 a0 = *(LAS const bf16x8*)(base + r * KST + (16 * s + 8 * h) * 2);
;                 const bf16x8 a1 = *(LAS const bf16x8*)(base + (32 + r) * KST + (16 * s + 8 * h) * 2);
;                 s0 = MFMA32(a0, qf[s], s0); s1 = MFMA32(a1, qf[s], s1);
;             }
;             float mx = s0[0];
; #pragma unroll
;             for (int i = 0; i < 16; ++i) { mx = fmaxf(mx, s0[i]); mx = fmaxf(mx, s1[i]); }
;             mx = fmaxf(mx, shx(mx, lane, 32));
;             const float m_new = fmaxf(m_run, mx), alpha = ex2(m_run - m_new);
;             m_run = m_new;
;             float ls = 0.f;
; #pragma unroll
;             for (int i = 0; i < 16; ++i) { s0[i] = ex2(s0[i] - m_new); s1[i] = ex2(s1[i] - m_new); ls += s0[i] + s1[i]; }
;             l_run = l_run * alpha + ls;
; #pragma unroll
;             for (int i = 0; i < 16; ++i) { o0[i] *= alpha; o1[i] *= alpha; }
;             LAS const unsigned char* vb = base + KB;
; #pragma unroll
;             for (int kt = 0; kt < 2; ++kt)
; #pragma unroll
;                 for (int ss = 0; ss < 2; ++ss) {
;                     const bf16x8 pb = packfrag(kt == 0 ? s0 : s1, ss);
;                     LAS const unsigned char* vp = vb + (32 * kt + 16 * ss + 4 * h + tq) * VST + (16 * blk + 4 * tp) * 2;
;                     const bf16x8 a0 = tr_frag(vp, 8 * VST), a1 = tr_frag(vp + 64, 8 * VST);
;                     o0 = MFMA32(a0, pb, o0); o1 = MFMA32(a1, pb, o1);
.LBB0_1012:
	s_or_b64 exec, exec, s[4:5]
	v_add_co_u32_e32 v212, vcc, 0x10000, v106
	s_nop 1
	v_addc_co_u32_e32 v213, vcc, 0, v107, vcc
	global_load_dword v200, v[212:213], off
	v_add_co_u32_e32 v214, vcc, 0x2110000, v106
	s_nop 1
	v_addc_co_u32_e32 v215, vcc, 0, v107, vcc
	global_load_dword v204, v[214:215], off
	v_add_u32_e32 v216, 64, v224
	v_mov_b32_e32 v217, 0
	v_lshlrev_b64 v[216:217], 6, v[216:217]
	v_lshl_add_u64 v[216:217], v[104:105], 0, v[216:217]
	global_load_dword v208, v[216:217], off
	v_cmp_lt_i32_e32 vcc, s7, v118
	s_and_saveexec_b64 s[4:5], vcc
	s_cbranch_execz .LBB0_1014
	s_bitcmp1_b32 s7, 0
	s_cselect_b32 s8, 0x5800, 0
	s_add_i32 s8, s8, 0
	v_add3_u32 v109, s8, v122, v100
	ds_read_b128 v[32:35], v109 offset:6656
	ds_read_b128 v[36:39], v109
	ds_read_b128 v[110:113], v109 offset:32
	ds_read_b128 v[124:127], v109 offset:6688
	s_waitcnt lgkmcnt(2)
	v_mfma_f32_32x32x16_bf16 v[48:63], v[36:39], v[84:87], 0
	v_mfma_f32_32x32x16_bf16 v[32:47], v[32:35], v[84:87], 0
	s_waitcnt lgkmcnt(1)
	v_mfma_f32_32x32x16_bf16 v[48:63], v[110:113], v[80:83], v[48:63]
	s_waitcnt lgkmcnt(0)
	v_mfma_f32_32x32x16_bf16 v[32:47], v[124:127], v[80:83], v[32:47]
	ds_read_b128 v[110:113], v109 offset:64
	ds_read_b128 v[124:127], v109 offset:6720
	s_waitcnt lgkmcnt(1)
	v_mfma_f32_32x32x16_bf16 v[48:63], v[110:113], v[76:79], v[48:63]
	s_waitcnt lgkmcnt(0)
	v_mfma_f32_32x32x16_bf16 v[32:47], v[124:127], v[76:79], v[32:47]
	ds_read_b128 v[110:113], v109 offset:96
	ds_read_b128 v[124:127], v109 offset:6752
	s_waitcnt lgkmcnt(1)
	v_mfma_f32_32x32x16_bf16 v[48:63], v[110:113], v[68:71], v[48:63]
	s_waitcnt lgkmcnt(0)
	v_mfma_f32_32x32x16_bf16 v[32:47], v[124:127], v[68:71], v[32:47]
	ds_read_b128 v[110:113], v109 offset:128
	ds_read_b128 v[124:127], v109 offset:6784
	s_waitcnt lgkmcnt(1)
	v_mfma_f32_32x32x16_bf16 v[48:63], v[110:113], v[72:75], v[48:63]
	s_waitcnt lgkmcnt(0)
	v_mfma_f32_32x32x16_bf16 v[32:47], v[124:127], v[72:75], v[32:47]
	ds_read_b128 v[110:113], v109 offset:160
	ds_read_b128 v[124:127], v109 offset:6816
	s_waitcnt lgkmcnt(1)
	v_mfma_f32_32x32x16_bf16 v[48:63], v[110:113], v[64:67], v[48:63]
	s_waitcnt lgkmcnt(0)
	v_mfma_f32_32x32x16_bf16 v[32:47], v[124:127], v[64:67], v[32:47]
	s_nop 9
	v_max_f32_e32 v110, v48, v48
	s_nop 0
	v_max_f32_e32 v109, v32, v32
	v_max_f32_e32 v109, v110, v109
	v_max3_f32 v109, v109, v49, v33
	v_max3_f32 v109, v109, v50, v34
	v_max3_f32 v109, v109, v51, v35
	v_max3_f32 v109, v109, v52, v36
	v_max3_f32 v109, v109, v53, v37
	v_max3_f32 v109, v109, v54, v38
	v_max3_f32 v109, v109, v55, v39
	v_max3_f32 v109, v109, v56, v40
	v_max3_f32 v109, v109, v57, v41
	v_max3_f32 v109, v109, v58, v42
	v_max3_f32 v109, v109, v59, v43
	v_max3_f32 v109, v109, v60, v44
	v_max3_f32 v109, v109, v61, v45
	v_max3_f32 v109, v109, v62, v46
	v_max3_f32 v109, v109, v63, v47
	ds_bpermute_b32 v110, v103, v109
	s_waitcnt lgkmcnt(0)
	v_max3_f32 v124, v108, v109, v110
	v_sub_f32_e32 v32, v32, v124
	v_exp_f32_e32 v125, v32
	v_sub_f32_e32 v32, v49, v124
	v_sub_f32_e32 v132, v108, v124
	v_exp_f32_e32 v108, v32
	v_sub_f32_e32 v32, v33, v124
	v_sub_f32_e32 v33, v50, v124
	v_exp_f32_e32 v134, v33
	v_sub_f32_e32 v33, v34, v124
	v_exp_f32_e32 v126, v33
	v_sub_f32_e32 v33, v51, v124
	v_sub_f32_e32 v48, v48, v124
	v_exp_f32_e32 v110, v33
	v_sub_f32_e32 v33, v35, v124
	v_exp_f32_e32 v133, v48
	v_exp_f32_e32 v48, v33
	v_sub_f32_e32 v33, v52, v124
	v_exp_f32_e32 v135, v33
	v_sub_f32_e32 v33, v36, v124
	v_exp_f32_e32 v127, v33
	v_sub_f32_e32 v33, v53, v124
	v_exp_f32_e32 v112, v33
	v_sub_f32_e32 v33, v37, v124
	v_exp_f32_e32 v50, v33
	v_sub_f32_e32 v33, v54, v124
	v_exp_f32_e32 v136, v33
	v_sub_f32_e32 v33, v38, v124
	v_exp_f32_e32 v129, v33
	v_sub_f32_e32 v33, v55, v124
	v_exp_f32_e32 v130, v33
	v_sub_f32_e32 v33, v39, v124
	v_exp_f32_e32 v52, v33
	v_sub_f32_e32 v33, v56, v124
	v_exp_f32_e32 v138, v33
	v_sub_f32_e32 v33, v40, v124
	v_exp_f32_e32 v35, v33
	v_sub_f32_e32 v33, v57, v124
	v_exp_f32_e32 v54, v33
	v_sub_f32_e32 v33, v41, v124
	v_exp_f32_e32 v36, v33
	v_sub_f32_e32 v33, v58, v124
	v_exp_f32_e32 v139, v33
	v_sub_f32_e32 v33, v42, v124
	v_exp_f32_e32 v128, v33
	v_sub_f32_e32 v33, v59, v124
	v_exp_f32_e32 v56, v33
	v_sub_f32_e32 v33, v43, v124
	v_exp_f32_e32 v38, v33
	v_sub_f32_e32 v33, v60, v124
	v_exp_f32_e32 v140, v33
	v_sub_f32_e32 v33, v44, v124
	v_exp_f32_e32 v60, v33
	v_sub_f32_e32 v33, v61, v124
	v_exp_f32_e32 v58, v33
	v_sub_f32_e32 v33, v45, v124
	v_exp_f32_e32 v40, v33
	v_sub_f32_e32 v33, v62, v124
	v_exp_f32_e32 v32, v32
	v_exp_f32_e32 v61, v33
	v_sub_f32_e32 v33, v46, v124
	v_exp_f32_e32 v46, v33
	v_sub_f32_e32 v33, v63, v124
	v_exp_f32_e32 v44, v33
	v_sub_f32_e32 v33, v47, v124
	v_add_f32_e32 v109, v133, v125
	v_exp_f32_e32 v42, v33
	v_mov_b32_e32 v33, v225
	v_pk_add_f32 v[62:63], v[108:109], v[32:33]
	v_add_f32_e32 v111, v134, v126
	v_pk_add_f32 v[62:63], v[62:63], v[62:63] op_sel_hi:[0,1]
	v_mov_b32_e32 v49, v63
	v_pk_add_f32 v[62:63], v[110:111], v[48:49]
	v_add_f32_e32 v113, v135, v127
	v_pk_add_f32 v[62:63], v[62:63], v[62:63] op_sel_hi:[0,1]
	v_mov_b32_e32 v51, v63
	v_pk_add_f32 v[62:63], v[112:113], v[50:51]
	v_add_f32_e32 v131, v136, v129
	v_pk_add_f32 v[62:63], v[62:63], v[62:63] op_sel_hi:[0,1]
	v_mov_b32_e32 v53, v63
	v_add3_u32 v47, s8, v116, v117
	v_exp_f32_e32 v34, v132
	v_pk_add_f32 v[62:63], v[130:131], v[52:53]
	v_cvt_pk_bf16_f32 v108, v133, v108
	v_cvt_pk_bf16_f32 v109, v134, v110
	v_cvt_pk_bf16_f32 v110, v135, v112
	v_cvt_pk_bf16_f32 v111, v136, v130
	ds_read_b64_tr_b16 v[130:131], v47 offset:13312
	ds_read_b64_tr_b16 v[132:133], v47 offset:14464
	ds_read_b64_tr_b16 v[134:135], v47 offset:13376
	ds_read_b64_tr_b16 v[136:137], v47 offset:14528
	v_pk_mul_f32 v[14:15], v[14:15], v[34:35] op_sel_hi:[1,0]
	v_pk_mul_f32 v[12:13], v[12:13], v[34:35] op_sel_hi:[1,0]
	v_pk_mul_f32 v[10:11], v[10:11], v[34:35] op_sel_hi:[1,0]
	v_pk_mul_f32 v[8:9], v[8:9], v[34:35] op_sel_hi:[1,0]
	v_pk_mul_f32 v[6:7], v[6:7], v[34:35] op_sel_hi:[1,0]
	v_pk_mul_f32 v[4:5], v[4:5], v[34:35] op_sel_hi:[1,0]
	v_pk_mul_f32 v[2:3], v[2:3], v[34:35] op_sel_hi:[1,0]
	v_pk_mul_f32 v[0:1], v[0:1], v[34:35] op_sel_hi:[1,0]
	v_pk_mul_f32 v[30:31], v[30:31], v[34:35] op_sel_hi:[1,0]
	v_pk_mul_f32 v[28:29], v[28:29], v[34:35] op_sel_hi:[1,0]
	v_pk_mul_f32 v[26:27], v[26:27], v[34:35] op_sel_hi:[1,0]
	v_pk_mul_f32 v[24:25], v[24:25], v[34:35] op_sel_hi:[1,0]
	v_pk_mul_f32 v[22:23], v[22:23], v[34:35] op_sel_hi:[1,0]
	v_pk_mul_f32 v[20:21], v[20:21], v[34:35] op_sel_hi:[1,0]
	v_pk_mul_f32 v[18:19], v[18:19], v[34:35] op_sel_hi:[1,0]
	v_pk_mul_f32 v[16:17], v[16:17], v[34:35] op_sel_hi:[1,0]
	s_waitcnt lgkmcnt(2)
; #define LAS __attribute__((address_space(3)))
; #define LBAR() do { asm volatile("s_waitcnt lgkmcnt(0)" ::: "memory"); __builtin_amdgcn_s_barrier(); asm volatile("" ::: "memory"); } while (0)
; #define MFMA32(a, b, c) __builtin_amdgcn_mfma_f32_32x32x16_bf16((a), (b), (c), 0, 0, 0)
; DI bf16x8 tr_frag(LAS const unsigned char* p, int hi_off) { s16x4 lo = trr(p), hi = trr(p + hi_off); return __builtin_shufflevector(lo, hi, 0, 1, 2, 3, 4, 5, 6, 7); }
; #define MLA_STORE(bi) do { LAS unsigned char* b_ = lds + (bi) * BUF; *(LAS u32x4*)(b_ + lk * KST + lc * 16) = gk; *(LAS u32x4*)(b_ + KB + lk * VST + lc * 16) = gv; \
;         if (tid < 256) *(LAS u32x4*)(b_ + rkk * KST + 128 + rc * 16) = gr; } while (0)
; DI void mla_item(int g_wave, LAS unsigned char* lds, const bf16_t* QN, const bf16_t* QR, const bf16_t* KN, const bf16_t* KRb, const bf16_t* VM, bf16_t* MIX,
;                  int kvbase, int qrow0, int nq, int head, int ntiles, int wt) {
;     ...
;             LAS const unsigned char* vb = base + KB;
; #pragma unroll
;             for (int kt = 0; kt < 2; ++kt)
; #pragma unroll
;                 for (int ss = 0; ss < 2; ++ss) {
;                     const bf16x8 pb = packfrag(kt == 0 ? s0 : s1, ss);
;                     LAS const unsigned char* vp = vb + (32 * kt + 16 * ss + 4 * h + tq) * VST + (16 * blk + 4 * tp) * 2;
;                     const bf16x8 a0 = tr_frag(vp, 8 * VST), a1 = tr_frag(vp + 64, 8 * VST);
;                     o0 = MFMA32(a0, pb, o0); o1 = MFMA32(a1, pb, o1);
;                 }
;         }
;         if (T + 1 < ntiles) MLA_STORE((T + 1) & 1);
;         LBAR();
	v_mfma_f32_32x32x16_bf16 v[0:15], v[130:133], v[108:111], v[0:15]
	v_pk_add_f32 v[62:63], v[62:63], v[62:63] op_sel_hi:[0,1]
	v_add_f32_e32 v55, v138, v35
	v_mov_b32_e32 v37, v63
	v_pk_add_f32 v[62:63], v[54:55], v[36:37]
	v_add_f32_e32 v57, v139, v128
	v_pk_add_f32 v[62:63], v[62:63], v[62:63] op_sel_hi:[0,1]
	v_mov_b32_e32 v39, v63
	s_waitcnt lgkmcnt(0)
	v_mfma_f32_32x32x16_bf16 v[16:31], v[134:137], v[108:111], v[16:31]
	ds_read_b64_tr_b16 v[108:109], v47 offset:15616
	ds_read_b64_tr_b16 v[110:111], v47 offset:16768
	ds_read_b64_tr_b16 v[130:131], v47 offset:15680
	ds_read_b64_tr_b16 v[132:133], v47 offset:16832
	v_add_f32_e64 v62, v56, v38
	v_add_f32_e64 v63, v57, v39
	v_cvt_pk_bf16_f32 v54, v138, v54
	v_cvt_pk_bf16_f32 v55, v139, v56
	v_cvt_pk_bf16_f32 v56, v140, v58
	v_cvt_pk_bf16_f32 v57, v61, v44
	v_pk_add_f32 v[62:63], v[62:63], v[62:63] op_sel_hi:[0,1]
	v_add_f32_e32 v59, v140, v60
	s_waitcnt lgkmcnt(2)
	v_mfma_f32_32x32x16_bf16 v[0:15], v[108:111], v[54:57], v[0:15]
	v_mov_b32_e32 v41, v63
	v_add_f32_e64 v62, v58, v40
	v_add_f32_e64 v63, v59, v41
	v_add_f32_e32 v45, v61, v46
	v_pk_add_f32 v[62:63], v[62:63], v[62:63] op_sel_hi:[0,1]
	v_mov_b32_e32 v43, v63
	v_pk_add_f32 v[62:63], v[44:45], v[42:43]
	v_cvt_pk_bf16_f32 v37, v128, v38
	s_waitcnt lgkmcnt(0)
	v_mfma_f32_32x32x16_bf16 v[16:31], v[130:133], v[54:57], v[16:31]
	v_cvt_pk_bf16_f32 v55, v126, v48
	v_cvt_pk_bf16_f32 v56, v127, v50
	ds_read_b64_tr_b16 v[48:49], v47 offset:17920
	ds_read_b64_tr_b16 v[50:51], v47 offset:19072
	ds_read_b64_tr_b16 v[108:109], v47 offset:17984
	ds_read_b64_tr_b16 v[110:111], v47 offset:19136
	v_cvt_pk_bf16_f32 v54, v125, v32
	v_cvt_pk_bf16_f32 v57, v129, v52
	v_cvt_pk_bf16_f32 v38, v60, v40
	v_cvt_pk_bf16_f32 v39, v46, v42
	s_waitcnt lgkmcnt(2)
	v_mfma_f32_32x32x16_bf16 v[0:15], v[48:51], v[54:57], v[0:15]
	ds_read_b64_tr_b16 v[40:41], v47 offset:20224
	ds_read_b64_tr_b16 v[42:43], v47 offset:21376
	ds_read_b64_tr_b16 v[44:45], v47 offset:20288
	ds_read_b64_tr_b16 v[46:47], v47 offset:21440
	v_cvt_pk_bf16_f32 v36, v35, v36
	v_add_f32_e32 v33, v62, v63
	v_fmac_f32_e32 v33, v115, v34
	v_mov_b32_e32 v115, v33
	s_waitcnt lgkmcnt(4)
	v_mfma_f32_32x32x16_bf16 v[16:31], v[108:111], v[54:57], v[16:31]
	v_mov_b32_e32 v108, v124
	s_waitcnt lgkmcnt(2)
	v_mfma_f32_32x32x16_bf16 v[0:15], v[40:43], v[36:39], v[0:15]
	s_waitcnt lgkmcnt(0)
	v_mfma_f32_32x32x16_bf16 v[16:31], v[44:47], v[36:39], v[16:31]
.LBB0_1014:
	s_or_b64 exec, exec, s[4:5]
	s_add_i32 s7, s7, 1
	s_bitcmp1_b32 s7, 0
	s_cselect_b32 s4, 0x5800, 0
	s_add_i32 s8, s4, 0
	v_add3_u32 v32, s8, v119, v102
	s_waitcnt vmcnt(4)
	ds_write_b128 v32, v[92:95]
	v_add3_u32 v32, s8, v123, v102
	s_waitcnt vmcnt(3)
	ds_write_b128 v32, v[96:99] offset:13312
	s_and_saveexec_b64 s[4:5], s[0:1]
	s_cbranch_execz .LBB0_1009
	v_add3_u32 v32, s8, v121, v120
	ds_write_b128 v32, v[88:91] offset:128
	s_branch .LBB0_1009
